# attention PV: the 20 V^T fragment LDS reads issued in bursts with counted lgkmcnt instead of read-wait-MFMA in series (on top of the QK^T burst)
# baseline (speedup 1.0000x reference)
.LBB0_752:
	s_or_b64 exec, exec, s[70:71]
	s_ashr_i32 s70, s78, 11
	s_lshl_b32 vcc_lo, s70, 1
	s_and_b32 s69, s78, 0x7f
	s_bfm_b32 s71, vcc_lo, 0
	s_and_b32 s71, s71, s69
	s_bfe_u32 s79, s78, 0x40007
	s_lshr_b32 s72, s69, vcc_lo
	v_add_u32_e32 v2, s68, v138
	s_add_u32 s64, s50, s64
	v_ashrrev_i32_e32 v3, 31, v2
	s_addc_u32 s65, s51, s65
	v_lshlrev_b64 v[2:3], 7, v[2:3]
	v_lshl_add_u64 v[2:3], s[64:65], 0, v[2:3]
	v_mov_b32_e32 v131, v1
	v_lshl_add_u64 v[2:3], v[2:3], 0, v[130:131]
	global_load_dwordx4 v[80:83], v[2:3], off
	global_load_dwordx4 v[84:87], v[2:3], off offset:64
	ds_read_b128 v[216:219], v141 offset:36864
	ds_read_b128 v[220:223], v141 offset:36928
	ds_read_b128 v[224:227], v142 offset:36864
	ds_read_b128 v[228:231], v142 offset:36928
	ds_read_b128 v[232:235], v143 offset:36864
	ds_read_b128 v[236:239], v143 offset:36928
	ds_read_b128 v[240:243], v144 offset:36864
	ds_read_b128 v[244:247], v144 offset:36928
	ds_read_b128 v[182:185], v145 offset:36864
	ds_read_b128 v[186:189], v145 offset:36928
	ds_read_b128 v[190:193], v146 offset:36864
	ds_read_b128 v[194:197], v146 offset:36928
	ds_read_b128 v[160:163], v147 offset:36864
	ds_read_b128 v[198:201], v147 offset:36928
	s_waitcnt vmcnt(13) lgkmcnt(13)
	v_mfma_f32_16x16x32_bf16 v[152:155], v[216:219], v[88:91], 0
	v_lshl_add_u32 v0, s72, 7, v138
	s_cmp_lg_u32 s72, 0
	s_cselect_b32 s100, 0, 0x80
	v_lshrrev_b32_e32 v178, 6, v202
	v_and_b32_e32 v179, 15, v202
	v_lshl_or_b32 v178, v178, 4, v179
	v_lshrrev_b32_e32 v179, 7, v202
	v_bfe_u32 v180, v202, 4, 2
	v_lshlrev_b32_e32 v180, 2, v180
	v_lshl_add_u32 v179, v179, 5, v180
	v_max_u32_e32 v180, s100, v178
	v_sub_u32_e32 v175, v179, v180
	v_sub_u32_e32 v176, v178, v180
	v_add_u32_e32 v176, 0x81, v176
	v_lshlrev_b32_e32 v0, vcc_lo, v0
	s_waitcnt vmcnt(12) lgkmcnt(12)
	v_mfma_f32_16x16x32_bf16 v[152:155], v[220:223], v[92:95], v[152:155]
	ds_read_b128 v[216:219], v148 offset:36864
	ds_read_b128 v[220:223], v148 offset:36928
	s_waitcnt lgkmcnt(13)
	v_mfma_f32_16x16x32_bf16 v[124:127], v[224:227], v[88:91], 0
	s_waitcnt lgkmcnt(12)
	v_mfma_f32_16x16x32_bf16 v[124:127], v[228:231], v[92:95], v[124:127]
	ds_read_b128 v[224:227], v149 offset:36864
	ds_read_b128 v[228:231], v149 offset:36928
	s_waitcnt lgkmcnt(13)
	v_mfma_f32_16x16x32_bf16 v[120:123], v[232:235], v[88:91], 0
	s_waitcnt lgkmcnt(12)
	v_mfma_f32_16x16x32_bf16 v[120:123], v[236:239], v[92:95], v[120:123]
	ds_read_b128 v[232:235], v150 offset:36864
	ds_read_b128 v[236:239], v150 offset:36928
	s_waitcnt lgkmcnt(13)
	v_mfma_f32_16x16x32_bf16 v[116:119], v[240:243], v[88:91], 0
	s_waitcnt lgkmcnt(12)
	v_mfma_f32_16x16x32_bf16 v[116:119], v[244:247], v[92:95], v[116:119]
	s_waitcnt lgkmcnt(11)
	v_mfma_f32_16x16x32_bf16 v[112:115], v[182:185], v[88:91], 0
	s_waitcnt lgkmcnt(10)
	v_mfma_f32_16x16x32_bf16 v[112:115], v[186:189], v[92:95], v[112:115]
	s_waitcnt lgkmcnt(9)
	v_mfma_f32_16x16x32_bf16 v[108:111], v[190:193], v[88:91], 0
	s_waitcnt lgkmcnt(8)
	v_mfma_f32_16x16x32_bf16 v[108:111], v[194:197], v[92:95], v[108:111]
	s_waitcnt lgkmcnt(7)
	v_mfma_f32_16x16x32_bf16 v[104:107], v[160:163], v[88:91], 0
	s_waitcnt lgkmcnt(6)
	v_mfma_f32_16x16x32_bf16 v[104:107], v[198:201], v[92:95], v[104:107]
	s_waitcnt lgkmcnt(5)
	v_mfma_f32_16x16x32_bf16 v[100:103], v[216:219], v[88:91], 0
	s_waitcnt lgkmcnt(4)
	v_mfma_f32_16x16x32_bf16 v[100:103], v[220:223], v[92:95], v[100:103]
	s_waitcnt lgkmcnt(3)
	v_mfma_f32_16x16x32_bf16 v[96:99], v[224:227], v[88:91], 0
	s_waitcnt lgkmcnt(2)
	v_mfma_f32_16x16x32_bf16 v[96:99], v[228:231], v[92:95], v[96:99]
	s_waitcnt lgkmcnt(1)
	v_mfma_f32_16x16x32_bf16 v[88:91], v[232:235], v[88:91], 0
	s_waitcnt lgkmcnt(0)
	v_mfma_f32_16x16x32_bf16 v[88:91], v[236:239], v[92:95], v[88:91]
	s_mov_b32 s68, 0xff61b1e6
	v_add_u32_e32 v177, 0, v175
	v_cmp_lt_u32_e32 vcc, v177, v176
	s_nop 1
	v_cndmask_b32_e32 v3, v213, v152, vcc
	v_add_u32_e32 v177, 1, v175
	v_cmp_lt_u32_e32 vcc, v177, v176
	s_nop 1
	v_cndmask_b32_e32 v2, v213, v153, vcc
	v_max3_f32 v94, v3, s68, v2
	v_add_u32_e32 v177, 2, v175
	v_cmp_lt_u32_e32 vcc, v177, v176
	s_nop 1
	v_cndmask_b32_e32 v92, v213, v154, vcc
	v_add_u32_e32 v177, 3, v175
	v_cmp_lt_u32_e32 vcc, v177, v176
	s_nop 1
	v_cndmask_b32_e32 v93, v213, v155, vcc
	v_add_u32_e32 v177, 16, v175
	v_cmp_lt_u32_e32 vcc, v177, v176
	s_nop 1
	v_cndmask_b32_e32 v95, v213, v124, vcc
	v_max3_f32 v129, v94, v92, v93
	v_add_u32_e32 v177, 17, v175
	v_cmp_lt_u32_e32 vcc, v177, v176
	s_nop 1
	v_cndmask_b32_e32 v94, v213, v125, vcc
	v_add_u32_e32 v177, 18, v175
	v_cmp_lt_u32_e32 vcc, v177, v176
	s_nop 1
	v_cndmask_b32_e32 v124, v213, v126, vcc
	v_add_u32_e32 v177, 19, v175
	v_cmp_lt_u32_e32 vcc, v177, v176
	s_nop 1
	v_cndmask_b32_e32 v125, v213, v127, vcc
	v_add_u32_e32 v177, 32, v175
	v_cmp_lt_u32_e32 vcc, v177, v176
	s_nop 1
	v_cndmask_b32_e32 v126, v213, v120, vcc
	v_add_u32_e32 v177, 33, v175
	v_cmp_lt_u32_e32 vcc, v177, v176
	s_nop 1
	v_cndmask_b32_e32 v120, v213, v121, vcc
	v_add_u32_e32 v177, 34, v175
	v_cmp_lt_u32_e32 vcc, v177, v176
	s_nop 1
	v_cndmask_b32_e32 v121, v213, v122, vcc
	v_add_u32_e32 v177, 35, v175
	v_cmp_lt_u32_e32 vcc, v177, v176
	s_nop 1
	v_cndmask_b32_e32 v122, v213, v123, vcc
	v_add_u32_e32 v177, 48, v175
	v_cmp_lt_u32_e32 vcc, v177, v176
	s_nop 1
	v_cndmask_b32_e32 v123, v213, v116, vcc
	v_add_u32_e32 v177, 49, v175
	v_cmp_lt_u32_e32 vcc, v177, v176
	s_nop 1
	v_cndmask_b32_e32 v116, v213, v117, vcc
	v_add_u32_e32 v177, 50, v175
	v_cmp_lt_u32_e32 vcc, v177, v176
	s_nop 1
	v_cndmask_b32_e32 v117, v213, v118, vcc
	v_add_u32_e32 v177, 51, v175
	v_cmp_lt_u32_e32 vcc, v177, v176
	s_nop 1
	v_cndmask_b32_e32 v118, v213, v119, vcc
	v_add_u32_e32 v177, 64, v175
	v_cmp_lt_u32_e32 vcc, v177, v176
	s_nop 1
	v_cndmask_b32_e32 v119, v213, v112, vcc
	v_add_u32_e32 v177, 0x41, v175
	v_cmp_lt_u32_e32 vcc, v177, v176
	s_nop 1
	v_cndmask_b32_e32 v112, v213, v113, vcc
	v_add_u32_e32 v177, 0x42, v175
	v_cmp_lt_u32_e32 vcc, v177, v176
	s_nop 1
	v_cndmask_b32_e32 v113, v213, v114, vcc
	v_add_u32_e32 v177, 0x43, v175
	v_cmp_lt_u32_e32 vcc, v177, v176
	s_nop 1
	v_cndmask_b32_e32 v114, v213, v115, vcc
	v_add_u32_e32 v177, 0x50, v175
	v_cmp_lt_u32_e32 vcc, v177, v176
	s_nop 1
	v_cndmask_b32_e32 v115, v213, v108, vcc
	v_add_u32_e32 v177, 0x51, v175
	v_cmp_lt_u32_e32 vcc, v177, v176
	s_nop 1
	v_cndmask_b32_e32 v108, v213, v109, vcc
	v_add_u32_e32 v177, 0x52, v175
	v_cmp_lt_u32_e32 vcc, v177, v176
	s_nop 1
	v_cndmask_b32_e32 v109, v213, v110, vcc
	v_add_u32_e32 v177, 0x53, v175
	v_cmp_lt_u32_e32 vcc, v177, v176
	s_nop 1
	v_cndmask_b32_e32 v110, v213, v111, vcc
	v_max3_f32 v129, v129, v95, v94
	v_add_u32_e32 v177, 0x60, v175
	v_cmp_lt_u32_e32 vcc, v177, v176
	s_nop 1
	v_cndmask_b32_e32 v111, v213, v104, vcc
	v_max3_f32 v127, v129, v124, v125
	v_max3_f32 v127, v127, v126, v120
	v_add_u32_e32 v177, 0x61, v175
	v_cmp_lt_u32_e32 vcc, v177, v176
	s_nop 1
	v_cndmask_b32_e32 v104, v213, v105, vcc
	v_max3_f32 v127, v127, v121, v122
	v_max3_f32 v127, v127, v123, v116
	v_max3_f32 v127, v127, v117, v118
	v_add_u32_e32 v177, 0x62, v175
	v_cmp_lt_u32_e32 vcc, v177, v176
	s_nop 1
	v_cndmask_b32_e32 v105, v213, v106, vcc
	v_max3_f32 v127, v127, v119, v112
	v_max3_f32 v127, v127, v113, v114
	v_max3_f32 v127, v127, v115, v108
	v_add_u32_e32 v177, 0x63, v175
	v_cmp_lt_u32_e32 vcc, v177, v176
	s_nop 1
	v_cndmask_b32_e32 v107, v213, v107, vcc
	v_max3_f32 v127, v127, v109, v110
	v_max3_f32 v127, v127, v111, v104
	v_max3_f32 v106, v127, v105, v107
	v_add_u32_e32 v177, 0x70, v175
	v_cmp_lt_u32_e32 vcc, v177, v176
	s_nop 1
	v_cndmask_b32_e32 v127, v213, v100, vcc
	v_add_u32_e32 v177, 0x71, v175
	v_cmp_lt_u32_e32 vcc, v177, v176
	s_nop 1
	v_cndmask_b32_e32 v100, v213, v101, vcc
	v_add_u32_e32 v177, 0x72, v175
	v_cmp_lt_u32_e32 vcc, v177, v176
	s_nop 1
	v_cndmask_b32_e32 v101, v213, v102, vcc
	v_add_u32_e32 v177, 0x73, v175
	v_cmp_lt_u32_e32 vcc, v177, v176
	s_nop 1
	v_cndmask_b32_e32 v102, v213, v103, vcc
	v_add_u32_e32 v177, 0x80, v175
	v_cmp_lt_u32_e32 vcc, v177, v176
	s_nop 1
	v_cndmask_b32_e32 v103, v213, v96, vcc
	v_add_u32_e32 v177, 0x81, v175
	v_cmp_lt_u32_e32 vcc, v177, v176
	s_nop 1
	v_cndmask_b32_e32 v96, v213, v97, vcc
	v_add_u32_e32 v177, 0x82, v175
	v_cmp_lt_u32_e32 vcc, v177, v176
	s_nop 1
	v_cndmask_b32_e32 v97, v213, v98, vcc
	v_add_u32_e32 v177, 0x83, v175
	v_cmp_lt_u32_e32 vcc, v177, v176
	s_nop 1
	v_cndmask_b32_e32 v99, v213, v99, vcc
	v_add_u32_e32 v177, 0x90, v175
	v_cmp_lt_u32_e32 vcc, v177, v176
	s_nop 1
	v_cndmask_b32_e32 v129, v213, v88, vcc
	v_max3_f32 v106, v106, v127, v100
	v_add_u32_e32 v177, 0x91, v175
	v_cmp_lt_u32_e32 vcc, v177, v176
	s_nop 1
	v_cndmask_b32_e32 v98, v213, v89, vcc
	v_max3_f32 v106, v106, v101, v102
	v_max3_f32 v106, v106, v103, v96
	v_max3_f32 v106, v106, v97, v99
	v_add_u32_e32 v177, 0x92, v175
	v_cmp_lt_u32_e32 vcc, v177, v176
	s_nop 1
	v_cndmask_b32_e32 v90, v213, v90, vcc
	v_max3_f32 v88, v106, v129, v98
	v_add_u32_e32 v177, 0x93, v175
	v_cmp_lt_u32_e32 vcc, v177, v176
	s_nop 1
	v_cndmask_b32_e32 v89, v213, v91, vcc
	v_cmp_lt_i32_e32 vcc, v209, v210
	v_max3_f32 v91, v88, v90, v89
	s_nop 0
	v_cndmask_b32_e32 v88, v208, v209, vcc
	v_lshlrev_b32_e32 v88, 2, v88
	ds_bpermute_b32 v106, v88, v91
	v_cmp_lt_i32_e32 vcc, v211, v210
	s_waitcnt lgkmcnt(0)
	v_max_f32_e32 v106, v106, v106
	v_max_f32_e32 v91, v91, v106
	v_cndmask_b32_e32 v106, v208, v211, vcc
	v_lshlrev_b32_e32 v131, 2, v106
	ds_bpermute_b32 v106, v131, v91
	s_waitcnt lgkmcnt(0)
	v_max_f32_e32 v106, v106, v106
	v_max_f32_e32 v106, v91, v106
	v_sub_f32_e32 v3, v3, v106
	v_mul_f32_e32 v3, 0x3fb8aa3b, v3
	v_sub_f32_e32 v2, v2, v106
	v_exp_f32_e32 v3, v3
	v_mul_f32_e32 v2, 0x3fb8aa3b, v2
	v_exp_f32_e32 v135, v2
	v_sub_f32_e32 v94, v94, v106
	v_add_f32_e32 v91, 0, v3
	v_mul_f32_e32 v94, 0x3fb8aa3b, v94
	v_add_f32_e32 v2, v135, v91
	v_sub_f32_e32 v91, v92, v106
	v_mul_f32_e32 v91, 0x3fb8aa3b, v91
	v_sub_f32_e32 v92, v93, v106
	v_exp_f32_e32 v91, v91
	v_mul_f32_e32 v92, 0x3fb8aa3b, v92
	v_sub_f32_e32 v93, v95, v106
	v_exp_f32_e32 v92, v92
	v_mul_f32_e32 v93, 0x3fb8aa3b, v93
	v_exp_f32_e32 v93, v93
	v_sub_f32_e32 v95, v124, v106
	v_exp_f32_e32 v94, v94
	v_mul_f32_e32 v95, 0x3fb8aa3b, v95
	v_sub_f32_e32 v124, v125, v106
	v_add_f32_e32 v2, v91, v2
	v_exp_f32_e32 v95, v95
	v_mul_f32_e32 v124, 0x3fb8aa3b, v124
	v_sub_f32_e32 v125, v126, v106
	v_add_f32_e32 v2, v92, v2
	v_exp_f32_e32 v124, v124
	v_mul_f32_e32 v125, 0x3fb8aa3b, v125
	v_sub_f32_e32 v120, v120, v106
	v_add_f32_e32 v2, v93, v2
	v_exp_f32_e32 v125, v125
	v_mul_f32_e32 v120, 0x3fb8aa3b, v120
	v_sub_f32_e32 v121, v121, v106
	v_add_f32_e32 v2, v94, v2
	v_exp_f32_e32 v120, v120
	v_mul_f32_e32 v121, 0x3fb8aa3b, v121
	v_sub_f32_e32 v122, v122, v106
	v_add_f32_e32 v2, v95, v2
	v_exp_f32_e32 v121, v121
	v_mul_f32_e32 v122, 0x3fb8aa3b, v122
	v_sub_f32_e32 v123, v123, v106
	v_add_f32_e32 v2, v124, v2
	v_exp_f32_e32 v122, v122
	v_mul_f32_e32 v123, 0x3fb8aa3b, v123
	v_sub_f32_e32 v116, v116, v106
	v_add_f32_e32 v2, v125, v2
	v_exp_f32_e32 v123, v123
	v_mul_f32_e32 v116, 0x3fb8aa3b, v116
	v_sub_f32_e32 v117, v117, v106
	v_sub_f32_e32 v112, v112, v106
	v_add_f32_e32 v2, v120, v2
	v_exp_f32_e32 v116, v116
	v_mul_f32_e32 v117, 0x3fb8aa3b, v117
	v_sub_f32_e32 v118, v118, v106
	v_mul_f32_e32 v112, 0x3fb8aa3b, v112
	v_add_f32_e32 v2, v121, v2
	v_exp_f32_e32 v117, v117
	v_mul_f32_e32 v118, 0x3fb8aa3b, v118
	v_sub_f32_e32 v119, v119, v106
	v_exp_f32_e32 v126, v112
	v_sub_f32_e32 v112, v113, v106
	v_add_f32_e32 v2, v122, v2
	v_exp_f32_e32 v118, v118
	v_mul_f32_e32 v119, 0x3fb8aa3b, v119
	v_mul_f32_e32 v112, 0x3fb8aa3b, v112
	v_add_f32_e32 v2, v123, v2
	v_exp_f32_e32 v119, v119
	v_exp_f32_e32 v152, v112
	v_sub_f32_e32 v112, v114, v106
	v_sub_f32_e32 v108, v108, v106
	v_add_f32_e32 v2, v116, v2
	v_mul_f32_e32 v112, 0x3fb8aa3b, v112
	v_mul_f32_e32 v108, 0x3fb8aa3b, v108
	v_add_f32_e32 v2, v117, v2
	v_exp_f32_e32 v153, v112
	v_sub_f32_e32 v112, v115, v106
	v_exp_f32_e32 v155, v108
	v_sub_f32_e32 v108, v109, v106
	v_add_f32_e32 v2, v118, v2
	v_mul_f32_e32 v112, 0x3fb8aa3b, v112
	v_mul_f32_e32 v108, 0x3fb8aa3b, v108
	v_add_f32_e32 v2, v119, v2
	v_exp_f32_e32 v154, v112
	v_exp_f32_e32 v160, v108
	v_sub_f32_e32 v108, v110, v106
	v_add_f32_e32 v2, v126, v2
	v_mul_f32_e32 v108, 0x3fb8aa3b, v108
	v_add_f32_e32 v2, v152, v2
	v_exp_f32_e32 v161, v108
	v_sub_f32_e32 v108, v111, v106
	v_add_f32_e32 v2, v153, v2
	v_mul_f32_e32 v108, 0x3fb8aa3b, v108
	v_sub_f32_e32 v104, v104, v106
	v_add_f32_e32 v2, v154, v2
	v_exp_f32_e32 v162, v108
	v_mul_f32_e32 v104, 0x3fb8aa3b, v104
	v_sub_f32_e32 v105, v105, v106
	v_sub_f32_e32 v100, v100, v106
	v_add_f32_e32 v2, v155, v2
	v_exp_f32_e32 v104, v104
	v_mul_f32_e32 v105, 0x3fb8aa3b, v105
	v_sub_f32_e32 v107, v107, v106
	v_mul_f32_e32 v100, 0x3fb8aa3b, v100
	v_add_f32_e32 v2, v160, v2
	v_exp_f32_e32 v105, v105
	v_mul_f32_e32 v107, 0x3fb8aa3b, v107
	v_sub_f32_e32 v108, v127, v106
	v_exp_f32_e32 v163, v100
	v_sub_f32_e32 v100, v101, v106
	v_add_f32_e32 v2, v161, v2
	v_exp_f32_e32 v107, v107
	v_mul_f32_e32 v108, 0x3fb8aa3b, v108
	v_mul_f32_e32 v100, 0x3fb8aa3b, v100
	v_sub_f32_e32 v96, v96, v106
	v_add_f32_e32 v2, v162, v2
	v_exp_f32_e32 v127, v108
	v_exp_f32_e32 v165, v100
	v_sub_f32_e32 v100, v102, v106
	v_mul_f32_e32 v96, 0x3fb8aa3b, v96
	v_add_f32_e32 v2, v104, v2
	v_mul_f32_e32 v100, 0x3fb8aa3b, v100
	v_exp_f32_e32 v168, v96
	v_sub_f32_e32 v96, v97, v106
	v_add_f32_e32 v2, v105, v2
	v_exp_f32_e32 v166, v100
	v_sub_f32_e32 v100, v103, v106
	v_mul_f32_e32 v96, 0x3fb8aa3b, v96
	v_add_f32_e32 v2, v107, v2
	v_mul_f32_e32 v100, 0x3fb8aa3b, v100
	v_exp_f32_e32 v169, v96
	v_sub_f32_e32 v96, v99, v106
	v_add_f32_e32 v2, v127, v2
	v_exp_f32_e32 v167, v100
	v_mul_f32_e32 v96, 0x3fb8aa3b, v96
	v_add_f32_e32 v2, v163, v2
	v_exp_f32_e32 v170, v96
	v_sub_f32_e32 v96, v129, v106
	v_add_f32_e32 v2, v165, v2
	v_mul_f32_e32 v96, 0x3fb8aa3b, v96
	v_add_f32_e32 v2, v166, v2
	v_exp_f32_e32 v129, v96
	v_sub_f32_e32 v96, v98, v106
	v_add_f32_e32 v2, v167, v2
	v_mul_f32_e32 v96, 0x3fb8aa3b, v96
	v_sub_f32_e32 v90, v90, v106
	v_add_f32_e32 v2, v168, v2
	v_exp_f32_e32 v171, v96
	v_mul_f32_e32 v90, 0x3fb8aa3b, v90
	v_sub_f32_e32 v89, v89, v106
	v_add_f32_e32 v2, v169, v2
	v_exp_f32_e32 v172, v90
	v_mul_f32_e32 v89, 0x3fb8aa3b, v89
	v_add_f32_e32 v2, v170, v2
	v_exp_f32_e32 v173, v89
	v_add_f32_e32 v2, v129, v2
	v_add_f32_e32 v2, v171, v2
	v_add_f32_e32 v2, v172, v2
	v_add_f32_e32 v2, v173, v2
	ds_bpermute_b32 v88, v88, v2
	v_cvt_pk_bf16_f32 v89, v91, v92
	v_cvt_pk_bf16_f32 v90, v93, v94
	v_cvt_pk_bf16_f32 v91, v95, v124
	v_add_u32_e32 v178, 0x2000, v151
	v_add_u32_e32 v179, 0x4000, v151
	v_add_u32_e32 v180, 0x6000, v151
	ds_read2_b64 v[216:219], v151 offset1:4
	ds_read2_b64 v[220:223], v178 offset0:68 offset1:72
	ds_read2_b64 v[224:227], v179 offset0:136 offset1:140
	ds_read2_b64 v[228:231], v180 offset0:204 offset1:208
	ds_read2_b64 v[232:235], v151 offset0:8 offset1:12
	ds_read2_b64 v[236:239], v178 offset0:76 offset1:80
	ds_read2_b64 v[240:243], v179 offset0:144 offset1:148
	ds_read2_b64 v[244:247], v180 offset0:212 offset1:216
	ds_read2_b64 v[182:185], v151 offset0:16 offset1:20
	ds_read2_b64 v[186:189], v178 offset0:84 offset1:88
	ds_read2_b64 v[190:193], v179 offset0:152 offset1:156
	ds_read2_b64 v[194:197], v180 offset0:220 offset1:224
	s_waitcnt lgkmcnt(12)
	v_add_f32_e32 v174, v2, v88
	v_add_u32_e32 v2, s71, v0
	v_cvt_pk_bf16_f32 v88, v3, v135
	v_add_u32_e32 v0, 0x2000, v151
	v_add_u32_e32 v3, 0x4000, v151
	v_add_u32_e32 v124, 0x6000, v151
	ds_bpermute_b32 v131, v131, v174
	s_ashr_i32 s71, s70, 31
	v_mov_b32_e32 v135, v1
	s_waitcnt lgkmcnt(12)
	v_mfma_f32_16x16x32_bf16 v[100:103], v[216:219], v[88:91], 0
	s_waitcnt lgkmcnt(11)
	v_mfma_f32_16x16x32_bf16 v[96:99], v[220:223], v[88:91], 0
	s_waitcnt lgkmcnt(10)
	v_mfma_f32_16x16x32_bf16 v[92:95], v[224:227], v[88:91], 0
	s_waitcnt lgkmcnt(9)
	v_mfma_f32_16x16x32_bf16 v[88:91], v[228:231], v[88:91], 0
	ds_read2_b64 v[216:219], v151 offset0:24 offset1:28
	ds_read2_b64 v[220:223], v178 offset0:92 offset1:96
	ds_read2_b64 v[224:227], v179 offset0:160 offset1:164
	ds_read2_b64 v[228:231], v180 offset0:228 offset1:232
	v_cvt_pk_bf16_f32 v108, v125, v120
	v_cvt_pk_bf16_f32 v109, v121, v122
	v_cvt_pk_bf16_f32 v110, v123, v116
	v_cvt_pk_bf16_f32 v111, v117, v118
	s_waitcnt lgkmcnt(12)
	s_nop 0
	v_mfma_f32_16x16x32_bf16 v[100:103], v[232:235], v[108:111], v[100:103]
	s_waitcnt lgkmcnt(11)
	v_mfma_f32_16x16x32_bf16 v[96:99], v[236:239], v[108:111], v[96:99]
	s_waitcnt lgkmcnt(10)
	v_mfma_f32_16x16x32_bf16 v[92:95], v[240:243], v[108:111], v[92:95]
	s_waitcnt lgkmcnt(9)
	v_mfma_f32_16x16x32_bf16 v[88:91], v[244:247], v[108:111], v[88:91]
	ds_read2_b64 v[232:235], v151 offset0:32 offset1:36
	ds_read2_b64 v[236:239], v178 offset0:100 offset1:104
	ds_read2_b64 v[240:243], v179 offset0:168 offset1:172
	ds_read2_b64 v[244:247], v180 offset0:236 offset1:240
	v_cvt_pk_bf16_f32 v108, v119, v126
	v_cvt_pk_bf16_f32 v109, v152, v153
	v_cvt_pk_bf16_f32 v110, v154, v155
	v_cvt_pk_bf16_f32 v111, v160, v161
	s_waitcnt lgkmcnt(12)
	s_nop 0
	v_mfma_f32_16x16x32_bf16 v[100:103], v[182:185], v[108:111], v[100:103]
	s_waitcnt lgkmcnt(11)
	v_mfma_f32_16x16x32_bf16 v[96:99], v[186:189], v[108:111], v[96:99]
	s_waitcnt lgkmcnt(10)
	v_mfma_f32_16x16x32_bf16 v[92:95], v[190:193], v[108:111], v[92:95]
	s_waitcnt lgkmcnt(9)
	v_mfma_f32_16x16x32_bf16 v[88:91], v[194:197], v[108:111], v[88:91]
	v_cvt_pk_bf16_f32 v108, v162, v104
	v_cvt_pk_bf16_f32 v109, v105, v107
	v_cvt_pk_bf16_f32 v110, v127, v163
	v_cvt_pk_bf16_f32 v111, v165, v166
	s_waitcnt lgkmcnt(8)
	v_add_f32_e32 v107, v174, v131
	s_waitcnt lgkmcnt(7)
	s_nop 0
	v_mfma_f32_16x16x32_bf16 v[100:103], v[216:219], v[108:111], v[100:103]
	s_waitcnt lgkmcnt(6)
	v_mfma_f32_16x16x32_bf16 v[96:99], v[220:223], v[108:111], v[96:99]
	s_waitcnt lgkmcnt(5)
	v_mfma_f32_16x16x32_bf16 v[92:95], v[224:227], v[108:111], v[92:95]
	s_waitcnt lgkmcnt(4)
	v_mfma_f32_16x16x32_bf16 v[88:91], v[228:231], v[108:111], v[88:91]
	v_cvt_pk_bf16_f32 v108, v167, v168
	v_cvt_pk_bf16_f32 v109, v169, v170
	v_cvt_pk_bf16_f32 v110, v129, v171
	v_cvt_pk_bf16_f32 v111, v172, v173
	v_div_scale_f32 v0, s[64:65], v107, v107, 1.0
	v_rcp_f32_e32 v3, v0
	s_lshl_b64 s[64:65], s[70:71], 25
	s_waitcnt lgkmcnt(3)
	s_nop 0
	v_mfma_f32_16x16x32_bf16 v[100:103], v[232:235], v[108:111], v[100:103]
	s_waitcnt lgkmcnt(2)
	v_mfma_f32_16x16x32_bf16 v[96:99], v[236:239], v[108:111], v[96:99]
	s_waitcnt lgkmcnt(1)
	v_mfma_f32_16x16x32_bf16 v[92:95], v[240:243], v[108:111], v[92:95]
	s_waitcnt lgkmcnt(0)
	v_mfma_f32_16x16x32_bf16 v[88:91], v[244:247], v[108:111], v[88:91]
	v_fma_f32 v104, -v0, v3, 1.0
	v_fmac_f32_e32 v3, v104, v3
	v_div_scale_f32 v104, vcc, 1.0, v107, 1.0
	v_mul_f32_e32 v105, v104, v3
	v_fma_f32 v108, -v0, v105, v104
	v_fmac_f32_e32 v105, v108, v3
	v_fma_f32 v0, -v0, v105, v104
	v_div_fmas_f32 v0, v0, v3, v105
	s_add_u32 s64, s52, s64
	v_ashrrev_i32_e32 v3, 31, v2
	s_addc_u32 s65, s53, s65
	v_lshlrev_b64 v[104:105], 11, v[2:3]
	v_div_fixup_f32 v0, v0, v107, 1.0
	v_lshl_add_u64 v[104:105], s[64:65], 0, v[104:105]
	s_lshl_b32 s72, s79, 7
	v_lshl_add_u64 v[104:105], v[104:105], 0, s[72:73]
	v_pk_mul_f32 v[100:101], v[0:1], v[100:101] op_sel_hi:[0,1]
	v_pk_mul_f32 v[102:103], v[0:1], v[102:103] op_sel_hi:[0,1]
	v_pk_mul_f32 v[96:97], v[0:1], v[96:97] op_sel_hi:[0,1]
	v_pk_mul_f32 v[98:99], v[0:1], v[98:99] op_sel_hi:[0,1]
	v_pk_mul_f32 v[92:93], v[0:1], v[92:93] op_sel_hi:[0,1]
	v_pk_mul_f32 v[94:95], v[0:1], v[94:95] op_sel_hi:[0,1]
	v_pk_mul_f32 v[88:89], v[0:1], v[88:89] op_sel_hi:[0,1]
	v_pk_mul_f32 v[90:91], v[0:1], v[90:91] op_sel_hi:[0,1]
	v_lshl_add_u64 v[104:105], v[104:105], 0, v[134:135]
	v_cvt_pk_bf16_f32 v100, v100, v101
	v_cvt_pk_bf16_f32 v101, v102, v103
	v_cvt_pk_bf16_f32 v96, v96, v97
	v_cvt_pk_bf16_f32 v97, v98, v99
	v_cvt_pk_bf16_f32 v92, v92, v93
	v_cvt_pk_bf16_f32 v93, v94, v95
	v_cvt_pk_bf16_f32 v88, v88, v89
	v_cvt_pk_bf16_f32 v89, v90, v91
	global_store_dwordx2 v[104:105], v[100:101], off
	global_store_dwordx2 v[104:105], v[96:97], off offset:32
	global_store_dwordx2 v[104:105], v[92:93], off offset:64
	global_store_dwordx2 v[104:105], v[88:89], off offset:96
	s_mov_b64 s[64:65], exec
	v_readlane_b32 s68, v255, 11
	v_readlane_b32 s69, v255, 12
	s_and_b64 s[68:69], s[64:65], s[68:69]
	s_mov_b64 exec, s[68:69]
	s_cbranch_execz .LBB0_749
	s_mov_b32 s68, 0x800000
	v_cmp_gt_f32_e32 vcc, s68, v107
	s_mov_b32 s68, 0x3f317217
	v_lshlrev_b64 v[2:3], 6, v[2:3]
	v_cndmask_b32_e64 v0, 0, 32, vcc
	v_ldexp_f32 v0, v107, v0
	v_log_f32_e32 v0, v0
	v_cndmask_b32_e32 v88, 0, v212, vcc
	v_mul_f32_e32 v89, 0x3f317217, v0
	v_fma_f32 v89, v0, s68, -v89
	s_mov_b32 s68, 0x7f800000
	v_fmac_f32_e32 v89, 0x3377d1cf, v0
	v_cmp_lt_f32_e64 vcc, |v0|, s68
	s_lshl_b64 s[68:69], s[70:71], 20
	v_fmac_f32_e32 v89, 0x3f317217, v0
	s_add_u32 s68, s55, s68
	v_readlane_b32 s70, v254, 44
	v_cndmask_b32_e32 v0, v0, v89, vcc
	s_addc_u32 s69, s70, s69
	v_sub_f32_e32 v0, v0, v88
	v_lshl_add_u64 v[2:3], s[68:69], 0, v[2:3]
	s_lshl_b32 s72, s79, 2
	v_add_f32_e32 v0, v106, v0
	v_lshl_add_u64 v[2:3], v[2:3], 0, s[72:73]
	global_store_dword v[2:3], v0, off
	s_branch .LBB0_749
